# barrier: L1 invalidate issued together with the arrival atomic; XCD-local release path skips the second invalidate and does not wait for the release atomic
# baseline (speedup 1.0000x reference)
.LBB0_88:
	s_lshl_b32 s1, s0, 8
	s_add_u32 s6, s48, s1
	s_addc_u32 s7, s49, 0
	v_mov_b32_e32 v1, 0x1000
	v_mov_b32_e32 v3, 1
	global_atomic_add v3, v1, v3, s[6:7] offset:1024 sc0
	buffer_inv sc1
	v_cvt_f32_u32_e32 v1, v2
	v_sub_u32_e32 v4, 0, v2
	v_rcp_iflag_f32_e32 v1, v1
	s_nop 0
	v_mul_f32_e32 v1, 0x4f7ffffe, v1
	v_cvt_u32_f32_e32 v1, v1
	v_mul_lo_u32 v4, v4, v1
	v_mul_hi_u32 v4, v1, v4
	v_add_u32_e32 v1, v1, v4
	s_waitcnt vmcnt(0)
	v_mul_hi_u32 v1, v3, v1
	v_mul_lo_u32 v4, v1, v2
	v_sub_u32_e32 v4, v3, v4
	v_add_u32_e32 v5, 1, v1
	v_cmp_ge_u32_e32 vcc, v4, v2
	v_add_u32_e32 v3, 1, v3
	s_nop 0
	v_cndmask_b32_e32 v1, v1, v5, vcc
	v_sub_u32_e32 v5, v4, v2
	v_cndmask_b32_e32 v4, v4, v5, vcc
	v_add_u32_e32 v5, 1, v1
	v_cmp_ge_u32_e32 vcc, v4, v2
	s_nop 1
	v_cndmask_b32_e32 v1, v1, v5, vcc
	v_mul_lo_u32 v4, v2, v1
	v_add_u32_e32 v2, v4, v2
	v_cmp_ne_u32_e32 vcc, v3, v2
	s_and_saveexec_b64 s[8:9], vcc
	s_xor_b64 s[8:9], exec, s[8:9]
	s_cbranch_execz .LBB0_102
	s_waitcnt lgkmcnt(0)
	v_mov_b32_e32 v0, 0x2000
	global_load_dword v0, v0, s[6:7] offset:1024 sc1
	s_add_u32 s14, s6, 0x2400
	s_addc_u32 s15, s7, 0
	s_waitcnt vmcnt(0)
	v_cmp_eq_u32_e32 vcc, v0, v1
	s_and_saveexec_b64 s[10:11], vcc
	s_cbranch_execz .LBB0_101
	v_readlane_b32 s12, v251, 7
	v_readlane_b32 s13, v251, 8
	s_load_dwordx2 s[12:13], s[12:13], 0xc8
	s_mov_b32 s1, 1
	s_mov_b64 s[16:17], 0
	v_mov_b32_e32 v0, 0
	s_waitcnt lgkmcnt(0)
	s_add_u32 s12, s12, 0x16900200
	s_addc_u32 s13, s13, 0
	s_branch .LBB0_92

.LBB0_124:
	s_or_b64 exec, exec, s[8:9]
	s_branch .Lgtail_d
.Lloc_d:
	v_readlane_b32 s2, v252, 49
	v_readlane_b32 s3, v252, 50
	s_nop 4
	global_atomic_add v197, v223, s[2:3]
	s_branch .LBB0_125

.LBB0_585:
	v_readlane_b32 s2, v252, 47
	v_readlane_b32 s3, v252, 48
	v_cvt_f32_u32_e32 v1, v2
	v_sub_u32_e32 v4, 0, v2
	v_rcp_iflag_f32_e32 v1, v1
	s_nop 1
	global_atomic_add v3, v197, v223, s[2:3] sc0
	buffer_inv sc1
	v_mul_f32_e32 v1, 0x4f7ffffe, v1
	v_cvt_u32_f32_e32 v1, v1
	v_mul_lo_u32 v4, v4, v1
	v_mul_hi_u32 v4, v1, v4
	v_add_u32_e32 v1, v1, v4
	s_waitcnt vmcnt(0)
	v_mul_hi_u32 v1, v3, v1
	v_mul_lo_u32 v4, v1, v2
	v_sub_u32_e32 v4, v3, v4
	v_add_u32_e32 v5, 1, v1
	v_cmp_ge_u32_e32 vcc, v4, v2
	v_add_u32_e32 v3, 1, v3
	s_nop 0
	v_cndmask_b32_e32 v1, v1, v5, vcc
	v_sub_u32_e32 v5, v4, v2
	v_cndmask_b32_e32 v4, v4, v5, vcc
	v_add_u32_e32 v5, 1, v1
	v_cmp_ge_u32_e32 vcc, v4, v2
	s_nop 1
	v_cndmask_b32_e32 v1, v1, v5, vcc
	v_mul_lo_u32 v4, v2, v1
	v_add_u32_e32 v2, v4, v2
	v_cmp_ne_u32_e32 vcc, v3, v2
	s_and_saveexec_b64 s[2:3], vcc
	s_xor_b64 s[8:9], exec, s[2:3]
	s_cbranch_execz .LBB0_599
	v_readlane_b32 s2, v252, 49
	v_readlane_b32 s3, v252, 50
	s_waitcnt lgkmcnt(0)
	s_nop 3
	global_load_dword v0, v197, s[2:3] sc1
	s_waitcnt vmcnt(0)
	v_cmp_eq_u32_e32 vcc, v0, v1
	s_and_saveexec_b64 s[12:13], vcc
	s_cbranch_execz .LBB0_598
	s_mov_b32 s1, 1
	s_mov_b64 s[18:19], 0
	s_branch .LBB0_589

.LBB0_639:
	v_readlane_b32 s2, v252, 47
	v_readlane_b32 s3, v252, 48
	v_cvt_f32_u32_e32 v1, v2
	v_sub_u32_e32 v4, 0, v2
	v_rcp_iflag_f32_e32 v1, v1
	s_nop 1
	global_atomic_add v3, v197, v223, s[2:3] sc0
	buffer_inv sc1
	v_mul_f32_e32 v1, 0x4f7ffffe, v1
	v_cvt_u32_f32_e32 v1, v1
	v_mul_lo_u32 v4, v4, v1
	v_mul_hi_u32 v4, v1, v4
	v_add_u32_e32 v1, v1, v4
	s_waitcnt vmcnt(0)
	v_mul_hi_u32 v1, v3, v1
	v_mul_lo_u32 v4, v1, v2
	v_sub_u32_e32 v4, v3, v4
	v_add_u32_e32 v5, 1, v1
	v_cmp_ge_u32_e32 vcc, v4, v2
	v_add_u32_e32 v3, 1, v3
	s_nop 0
	v_cndmask_b32_e32 v1, v1, v5, vcc
	v_sub_u32_e32 v5, v4, v2
	v_cndmask_b32_e32 v4, v4, v5, vcc
	v_add_u32_e32 v5, 1, v1
	v_cmp_ge_u32_e32 vcc, v4, v2
	s_nop 1
	v_cndmask_b32_e32 v1, v1, v5, vcc
	v_mul_lo_u32 v4, v2, v1
	v_add_u32_e32 v2, v4, v2
	v_cmp_ne_u32_e32 vcc, v3, v2
	s_and_saveexec_b64 s[2:3], vcc
	s_xor_b64 s[8:9], exec, s[2:3]
	s_cbranch_execz .LBB0_653
	v_readlane_b32 s2, v252, 49
	v_readlane_b32 s3, v252, 50
	s_waitcnt lgkmcnt(0)
	s_nop 3
	global_load_dword v0, v197, s[2:3] sc1
	s_waitcnt vmcnt(0)
	v_cmp_eq_u32_e32 vcc, v0, v1
	s_and_saveexec_b64 s[12:13], vcc
	s_cbranch_execz .LBB0_652
	s_mov_b32 s26, s30
	s_mov_b32 s1, 1
	s_mov_b64 s[18:19], 0
	s_branch .LBB0_643

.LBB0_895:
	v_readlane_b32 s2, v252, 47
	v_readlane_b32 s3, v252, 48
	v_cvt_f32_u32_e32 v1, v2
	v_sub_u32_e32 v4, 0, v2
	v_rcp_iflag_f32_e32 v1, v1
	s_nop 1
	global_atomic_add v3, v197, v223, s[2:3] sc0
	buffer_inv sc1
	v_mul_f32_e32 v1, 0x4f7ffffe, v1
	v_cvt_u32_f32_e32 v1, v1
	v_mul_lo_u32 v4, v4, v1
	v_mul_hi_u32 v4, v1, v4
	v_add_u32_e32 v1, v1, v4
	s_waitcnt vmcnt(0)
	v_mul_hi_u32 v1, v3, v1
	v_mul_lo_u32 v4, v1, v2
	v_sub_u32_e32 v4, v3, v4
	v_add_u32_e32 v5, 1, v1
	v_cmp_ge_u32_e32 vcc, v4, v2
	v_add_u32_e32 v3, 1, v3
	s_nop 0
	v_cndmask_b32_e32 v1, v1, v5, vcc
	v_sub_u32_e32 v5, v4, v2
	v_cndmask_b32_e32 v4, v4, v5, vcc
	v_add_u32_e32 v5, 1, v1
	v_cmp_ge_u32_e32 vcc, v4, v2
	s_nop 1
	v_cndmask_b32_e32 v1, v1, v5, vcc
	v_mul_lo_u32 v4, v2, v1
	v_add_u32_e32 v2, v4, v2
	v_cmp_ne_u32_e32 vcc, v3, v2
	s_and_saveexec_b64 s[2:3], vcc
	s_xor_b64 s[8:9], exec, s[2:3]
	s_cbranch_execz .LBB0_909
	v_readlane_b32 s2, v252, 49
	v_readlane_b32 s3, v252, 50
	s_waitcnt lgkmcnt(0)
	s_nop 3
	global_load_dword v0, v197, s[2:3] sc1
	s_waitcnt vmcnt(0)
	v_cmp_eq_u32_e32 vcc, v0, v1
	s_and_saveexec_b64 s[12:13], vcc
	s_cbranch_execz .LBB0_908
	s_mov_b32 s26, s30
	s_mov_b32 s2, 1
	s_mov_b64 s[18:19], 0
	s_branch .LBB0_899
